# adds: MLA tile loop stages the next K/V tile into LDS after the current tile's compute instead of before the barrier
# speedup vs baseline: 1.0134x; 1.0105x over previous
; #define LAS __attribute__((address_space(3)))
; __device__ __forceinline__ int otid() { int t = threadIdx.x; asm volatile("" : "+v"(t)); return t; }
; #define LDS_BARRIER() do { asm volatile("s_waitcnt lgkmcnt(0)" ::: "memory"); __builtin_amdgcn_s_barrier(); asm volatile("" ::: "memory"); } while (0)
; template <bool DRY> __device__ __forceinline__ void mla_unit(LAS unsigned char* lds, int b, int h, int qb, const bf16_t* Q, const bf16_t* Kn, const bf16_t* Pm, const bf16_t* VT, bf16_t* Y) {
;     const int tid = otid(), lane = tid & 63, r32 = lane & 31, hi = lane >> 5; const int wid = __builtin_amdgcn_readfirstlane(tid >> 6);
;     const int NT = 4 * qb + 4, tmax = 4 * qb + (wid >> 1);
;     const size_t tok0 = (size_t)b * SEQ;
;     const size_t qtok = tok0 + qb * 256 + wid * 32 + r32;
;     const bf16_t* qrow = Q + qtok * 768;
;     bf16x8 qf[6];
; #pragma unroll
;     for (int s = 0; s < 4; ++s) qf[s] = *(const bf16x8*)(qrow + h * 64 + 16 * s + 8 * hi);
; #pragma unroll
;     for (int s = 0; s < 2; ++s) qf[4 + s] = *(const bf16x8*)(qrow + 512 + h * 32 + 16 * s + 8 * hi);
;     const int ka_row = tid >> 3, ka_c = tid & 7, kb_row = (tid & 255) >> 2, kb_c = tid & 3;
;     const bf16_t* ka_src = Kn + (tok0 + ka_row) * 512 + h * 64 + ka_c * 8;
;     const bf16_t* kb_src = Pm + (tok0 + kb_row) * PW + PC_KR + kb_c * 8;
;     const bf16_t* va_src = VT + (size_t)(h * 64 + ka_row) * VTLD + tok0 + ka_c * 8;
;     const int ka_dst = ka_row * MLA_KSTR + ka_c * 16, kb_dst = kb_row * MLA_KSTR + 128 + kb_c * 16, va_dst = ka_row * MLA_VSTR + ka_c * 16;
;     u32x4 ra = *(const u32x4*)ka_src, rb = *(const u32x4*)kb_src, rv = *(const u32x4*)va_src;
;     float m_run = -1e30f, l_run = 0.f; f32x16 o0 = {}, o1 = {};
;     const float C = 0.10206207261596577f * 1.4426950408889634f;
;     for (int t = 0; t < NT; ++t) {
;         LAS unsigned char* kbuf = lds + (t & 1) * MLA_KB; LAS unsigned char* vbuf = lds + 2 * MLA_KB + (t & 1) * MLA_VB;
;         *(LAS u32x4*)(kbuf + ka_dst) = ra; if (tid < 256) *(LAS u32x4*)(kbuf + kb_dst) = rb; *(LAS u32x4*)(vbuf + va_dst) = rv;
;         LDS_BARRIER();
;         if (t + 1 < NT) { ra = *(const u32x4*)(ka_src + (size_t)(t + 1) * 64 * 512); rb = *(const u32x4*)(kb_src + (size_t)(t + 1) * 64 * PW); rv = *(const u32x4*)(va_src + (t + 1) * 64); }
.LBB0_801:
	s_lshr_b32 s22, s55, 1
	s_or_b32 s22, s22, s53
	s_and_b32 s23, s55, 1
	s_sub_i32 s28, 7, s22
	v_mov_b32_e32 v3, v234
	s_cmp_eq_u32 s23, 0
	s_cselect_b32 s42, s22, s28
	v_readfirstlane_b32 s43, v3
	v_and_b32_e32 v14, 31, v3
	s_ashr_i32 s22, s43, 1
	s_andn2_b32 s22, s22, 31
	v_lshl_or_b32 v0, s42, 8, v14
	s_ashr_i32 s23, s22, 31
	v_or_b32_e32 v0, s10, v0
	v_mov_b32_e32 v1, s11
	v_lshl_add_u64 v[0:1], v[0:1], 0, s[22:23]
	v_mov_b64_e32 v[4:5], s[8:9]
	v_bfe_u32 v16, v3, 2, 6
	v_mad_u64_u32 v[4:5], s[22:23], v0, s21, v[4:5]
	v_ashrrev_i32_e32 v6, 3, v3
	v_lshlrev_b32_e32 v12, 4, v3
	v_or_b32_e32 v13, s10, v16
	v_mov_b64_e32 v[10:11], s[6:7]
	v_bfe_u32 v15, v3, 5, 1
	v_mad_i32_i24 v5, v1, s21, v5
	s_lshl_b32 s28, s54, 1
	v_and_b32_e32 v110, 0x70, v12
	v_mad_u64_u32 v[10:11], s[22:23], v13, s24, v[10:11]
	v_and_b32_e32 v112, 48, v12
	v_add_u32_e32 v17, s54, v6
	v_mov_b64_e32 v[12:13], s[14:15]
	v_lshl_add_u64 v[104:105], v[4:5], 0, s[28:29]
	v_lshlrev_b32_e32 v108, 4, v15
	v_mov_b32_e32 v109, v2
	s_mov_b32 s41, s29
	v_ashrrev_i32_e32 v7, 31, v6
	v_mad_i32_i24 v11, s11, v240, v11
	v_mov_b32_e32 v113, v2
	v_mad_i64_i32 v[12:13], s[22:23], v17, s37, v[12:13]
	v_lshl_add_u64 v[0:1], v[104:105], 0, v[108:109]
	v_lshl_add_u64 v[4:5], v[4:5], 0, s[40:41]
	v_lshl_add_u64 v[8:9], s[10:11], 0, v[6:7]
	v_mov_b32_e32 v111, v2
	v_lshl_add_u64 v[10:11], v[10:11], 0, v[112:113]
	s_mov_b32 s22, 0x8101000
	global_load_dwordx4 v[68:71], v[0:1], off offset:32
	global_load_dwordx4 v[72:75], v[0:1], off offset:64
	v_lshl_add_u64 v[4:5], v[4:5], 0, v[108:109]
	global_load_dwordx4 v[76:79], v[0:1], off offset:96
	global_load_dwordx4 v[80:83], v[4:5], off offset:1024
	v_lshlrev_b64 v[8:9], 10, v[8:9]
	v_lshl_add_u64 v[114:115], v[12:13], 0, v[110:111]
	global_load_dwordx4 v[84:87], v[0:1], off
	global_load_dwordx4 v[88:91], v[114:115], off
	v_add_co_u32_e32 v0, vcc, s22, v10
	v_lshl_add_u64 v[8:9], s[12:13], 0, v[8:9]
	s_nop 0
	v_addc_co_u32_e32 v1, vcc, 0, v11, vcc
	v_lshl_add_u64 v[8:9], v[8:9], 0, v[110:111]
	global_load_dwordx4 v[96:99], v[0:1], off offset:3328
	global_load_dwordx4 v[92:95], v[4:5], off offset:1056
	global_load_dwordx4 v[100:103], v[8:9], off
	s_lshl_b32 s22, s42, 2
	s_ashr_i32 s56, s43, 7
	v_mul_u32_u24_e32 v0, 0x1d40, v16
	s_add_i32 s41, s22, 4
	s_add_i32 s56, s56, s22
	s_movk_i32 s22, 0xd0
	v_mul_hi_u32_u24_e32 v1, 0x1d40, v16
	v_or_b32_e32 v0, v0, v112
	v_mul_lo_u32 v107, v6, s22
	s_movk_i32 s22, 0x90
	v_lshl_add_u64 v[116:117], s[34:35], 0, v[0:1]
	v_lshlrev_b64 v[0:1], 10, v[6:7]
	v_lshlrev_b32_e32 v106, 3, v15
	v_mul_lo_u32 v111, v6, s22
	s_movk_i32 s22, 0x100
	v_mul_u32_u24_e32 v113, 0xd0, v14
	v_mul_u32_u24_e32 v120, 0x90, v14
	v_or_b32_e32 v0, v0, v110
	v_mov_b32_e32 v14, v2
	v_mov_b32_e32 v15, v2
	v_cmp_gt_i32_e64 s[42:43], s22, v3
	v_lshl_add_u64 v[118:119], s[38:39], 0, v[0:1]
	v_mov_b32_e32 v0, v2
	v_mov_b32_e32 v1, v2
	v_mov_b32_e32 v3, v2
	v_mov_b32_e32 v4, v2
	v_mov_b32_e32 v5, v2
	v_mov_b32_e32 v6, v2
	v_mov_b32_e32 v7, v2
	v_mov_b32_e32 v8, v2
	v_mov_b32_e32 v9, v2
	v_mov_b32_e32 v10, v2
	v_mov_b32_e32 v11, v2
	v_mov_b32_e32 v12, v2
	v_mov_b32_e32 v13, v2
	v_mov_b64_e32 v[34:35], v[14:15]
	v_mul_u32_u24_e32 v109, 0xd0, v16
	v_mov_b64_e32 v[32:33], v[12:13]
	v_mov_b64_e32 v[30:31], v[10:11]
	v_mov_b64_e32 v[28:29], v[8:9]
	v_mov_b64_e32 v[26:27], v[6:7]
	v_mov_b64_e32 v[24:25], v[4:5]
	v_mov_b64_e32 v[22:23], v[2:3]
	v_mov_b64_e32 v[20:21], v[0:1]
	v_mov_b64_e32 v[18:19], v[14:15]
	v_mov_b32_e32 v122, 0xf149f2ca
	v_mov_b32_e32 v121, 0
	s_mov_b32 s28, 64
	v_mov_b64_e32 v[16:17], v[12:13]
	v_mov_b64_e32 v[14:15], v[10:11]
	v_mov_b64_e32 v[12:13], v[8:9]
	v_mov_b64_e32 v[10:11], v[6:7]
	v_mov_b64_e32 v[8:9], v[4:5]
	v_mov_b64_e32 v[6:7], v[2:3]
	v_mov_b64_e32 v[4:5], v[0:1]
	s_mov_b32 s57, 0
	s_and_b32 s59, s57, 1
	s_mul_i32 s22, s59, 0x3400
	s_add_i32 s58, s22, 0
	v_add3_u32 v0, s58, v107, v110
	s_waitcnt vmcnt(0)
	ds_write_b128 v0, v[100:103]
	s_and_saveexec_b64 s[22:23], s[42:43]
	v_add3_u32 v0, s58, v109, v112
	ds_write_b128 v0, v[96:99] offset:128
	s_or_b64 exec, exec, s[22:23]
	s_lshl_b32 s22, s59, 12
	s_sub_i32 s23, s58, s22
	v_add3_u32 v0, s23, v111, v110
	ds_write_b128 v0, v[88:91] offset:26624
.LBB0_802:
	s_and_b32 s59, s57, 1
	s_mul_i32 s22, s59, 0x3400
	s_add_i32 s58, s22, 0
	s_lshl_b32 s22, s59, 12
	s_sub_i32 s23, s58, s22
	s_waitcnt lgkmcnt(0)
	s_barrier
	s_add_i32 s22, s57, 1
	s_cmp_ge_u32 s22, s41
	s_cbranch_scc1 .LBB0_806
	v_lshl_add_u64 v[0:1], s[28:29], 1, v[114:115]
	global_load_dwordx4 v[100:103], v[118:119], off
	global_load_dwordx4 v[96:99], v[116:117], off
	global_load_dwordx4 v[88:91], v[0:1], off

; #define LAS __attribute__((address_space(3)))
; #define LDS_BARRIER() do { asm volatile("s_waitcnt lgkmcnt(0)" ::: "memory"); __builtin_amdgcn_s_barrier(); asm volatile("" ::: "memory"); } while (0)
; template <bool DRY> __device__ __forceinline__ void mla_unit(LAS unsigned char* lds, int b, int h, int qb, const bf16_t* Q, const bf16_t* Kn, const bf16_t* Pm, const bf16_t* VT, bf16_t* Y) {
;     ...
;     for (int t = 0; t < NT; ++t) {
;         LAS unsigned char* kbuf = lds + (t & 1) * MLA_KB; LAS unsigned char* vbuf = lds + 2 * MLA_KB + (t & 1) * MLA_VB;
;         *(LAS u32x4*)(kbuf + ka_dst) = ra; if (tid < 256) *(LAS u32x4*)(kbuf + kb_dst) = rb; *(LAS u32x4*)(vbuf + va_dst) = rv;
;         LDS_BARRIER();
;         if (t + 1 < NT) { ra = *(const u32x4*)(ka_src + (size_t)(t + 1) * 64 * 512); rb = *(const u32x4*)(kb_src + (size_t)(t + 1) * 64 * PW); rv = *(const u32x4*)(va_src + (t + 1) * 64); }
.LBB0_811:
	s_mov_b64 s[58:59], 0x75000
	v_lshl_add_u64 v[116:117], v[116:117], 0, s[58:59]
	s_add_i32 s28, s28, 64
	s_mov_b64 s[58:59], 0x10000
	s_cmp_lg_u32 s41, s22
	v_lshl_add_u64 v[118:119], v[118:119], 0, s[58:59]
	s_cbranch_scc0 .LBB0_800
	v_mov_b32_e32 v122, v0
	s_mov_b32 s57, s22
	s_and_b32 s59, s57, 1
	s_mul_i32 s22, s59, 0x3400
	s_add_i32 s58, s22, 0
	v_add3_u32 v0, s58, v107, v110
	s_waitcnt vmcnt(0)
	ds_write_b128 v0, v[100:103]
	s_and_saveexec_b64 s[22:23], s[42:43]
	v_add3_u32 v0, s58, v109, v112
	ds_write_b128 v0, v[96:99] offset:128
	s_or_b64 exec, exec, s[22:23]
	s_lshl_b32 s22, s59, 12
	s_sub_i32 s23, s58, s22
	v_add3_u32 v0, s23, v111, v110
	ds_write_b128 v0, v[88:91] offset:26624
	s_branch .LBB0_802
